# W_o GEMM epilogue: all gate / accumulator chunks of the tile touched up front (cache warm) before the compiler's per-chunk load-use sequence
# baseline (speedup 1.0000x reference)
; __device__ __forceinline__ u32x4 pack8(f32x4 a, f32x4 b) { u32x4 o; o.x = pk2(a[0], a[1]); o.y = pk2(a[2], a[3]); o.z = pk2(b[0], b[1]); o.w = pk2(b[2], b[3]); return o; }
; __device__ __forceinline__ void unpack8(u32x4 v, f32x4& a, f32x4& b) { a[0] = bflo(v.x); a[1] = bfhi(v.x); a[2] = bflo(v.y); a[3] = bfhi(v.y); b[0] = bflo(v.z); b[1] = bfhi(v.z); b[2] = bflo(v.w); b[3] = bfhi(v.w); }
;     __device__ __forceinline__ void operator()(AccRef acc, const Unit& u, int wr, int wc, int fr, int fq) const {
;         const int row0 = u.pm * 256 + wr * 64 + fr, col0 = u.pn * 256 + wc * 32 + 8 * fq;
; #pragma unroll
;         for (int ai = 0; ai < 2; ++ai)
; #pragma unroll
;             for (int m = 0; m < 4; ++m)
; #pragma unroll
;                 for (int bj = 0; bj < 2; ++bj) { const size_t off = (size_t)(row0 + ai * 128 + m * 16) * 2048 + col0 + bj * 128;
;                     f32x4 g0, g1, o0, o1, a, b; unpack8(*(const u32x4*)(GB + off), g0, g1); unpack8(*(const u32x4*)(O + off), o0, o1);
; #pragma unroll
;                     for (int i = 0; i < 4; ++i) { a[i] = o0[i] + g0[i] * acc[ai][bj][m][0][i]; b[i] = o1[i] + g1[i] * acc[ai][bj][m][1][i]; }
;                     *(u32x4*)(O + off) = pack8(a, b); }
.LBB0_1703:
	v_lshl_add_u32 v148, s60, 8, v150
	v_lshl_or_b32 v146, s75, 8, v152
	v_ashrrev_i32_e32 v149, 31, v148
	v_ashrrev_i32_e32 v147, 31, v146
	v_lshlrev_b64 v[144:145], 11, v[148:149]
	v_lshl_add_u64 v[144:145], v[144:145], 0, v[146:147]
	v_lshlrev_b64 v[144:145], 1, v[144:145]
	global_load_dwordx4 v[188:191], v144, s[44:45] offset:0
	global_load_dwordx4 v[192:195], v144, s[36:37] offset:0
	global_load_dwordx4 v[188:191], v144, s[44:45] offset:256
	global_load_dwordx4 v[192:195], v144, s[36:37] offset:256
	v_add_u32_e32 v196, 0x10000, v144
	global_load_dwordx4 v[188:191], v196, s[44:45] offset:0
	global_load_dwordx4 v[192:195], v196, s[36:37] offset:0
	global_load_dwordx4 v[188:191], v196, s[44:45] offset:256
	global_load_dwordx4 v[192:195], v196, s[36:37] offset:256
	v_add_u32_e32 v196, 0x20000, v144
	global_load_dwordx4 v[188:191], v196, s[44:45] offset:0
	global_load_dwordx4 v[192:195], v196, s[36:37] offset:0
	global_load_dwordx4 v[188:191], v196, s[44:45] offset:256
	global_load_dwordx4 v[192:195], v196, s[36:37] offset:256
	v_add_u32_e32 v196, 0x30000, v144
	global_load_dwordx4 v[188:191], v196, s[44:45] offset:0
	global_load_dwordx4 v[192:195], v196, s[36:37] offset:0
	global_load_dwordx4 v[188:191], v196, s[44:45] offset:256
	global_load_dwordx4 v[192:195], v196, s[36:37] offset:256
	v_add_u32_e32 v196, 0x80000, v144
	global_load_dwordx4 v[188:191], v196, s[44:45] offset:0
	global_load_dwordx4 v[192:195], v196, s[36:37] offset:0
	global_load_dwordx4 v[188:191], v196, s[44:45] offset:256
	global_load_dwordx4 v[192:195], v196, s[36:37] offset:256
	v_add_u32_e32 v196, 0x90000, v144
	global_load_dwordx4 v[188:191], v196, s[44:45] offset:0
	global_load_dwordx4 v[192:195], v196, s[36:37] offset:0
	global_load_dwordx4 v[188:191], v196, s[44:45] offset:256
	global_load_dwordx4 v[192:195], v196, s[36:37] offset:256
	v_add_u32_e32 v196, 0xa0000, v144
	global_load_dwordx4 v[188:191], v196, s[44:45] offset:0
	global_load_dwordx4 v[192:195], v196, s[36:37] offset:0
	global_load_dwordx4 v[188:191], v196, s[44:45] offset:256
	global_load_dwordx4 v[192:195], v196, s[36:37] offset:256
	v_add_u32_e32 v196, 0xb0000, v144
	global_load_dwordx4 v[188:191], v196, s[44:45] offset:0
	global_load_dwordx4 v[192:195], v196, s[36:37] offset:0
	global_load_dwordx4 v[188:191], v196, s[44:45] offset:256
	global_load_dwordx4 v[192:195], v196, s[36:37] offset:256
	v_lshl_add_u64 v[156:157], s[44:45], 0, v[144:145]
	v_lshl_add_u64 v[164:165], s[36:37], 0, v[144:145]
	global_load_dwordx4 v[156:159], v[156:157], off
	v_or_b32_e32 v166, 0x100, v144
	global_load_dwordx4 v[160:163], v[164:165], off
	v_mov_b32_e32 v167, v145
	v_lshl_add_u64 v[168:169], s[44:45], 0, v[166:167]
	s_mov_b64 s[42:43], 0x80000
	s_andn2_b64 vcc, exec, s[0:1]
	s_mov_b64 s[0:1], -1
	s_waitcnt vmcnt(0)
	v_lshlrev_b32_e32 v149, 16, v156
	v_and_b32_e32 v156, 0xffff0000, v156
	v_lshlrev_b32_e32 v170, 16, v157
	v_and_b32_e32 v157, 0xffff0000, v157
	v_lshlrev_b32_e32 v173, 16, v160
	v_and_b32_e32 v160, 0xffff0000, v160
	v_lshlrev_b32_e32 v174, 16, v161
	v_and_b32_e32 v161, 0xffff0000, v161
	v_lshlrev_b32_e32 v171, 16, v158
	v_and_b32_e32 v158, 0xffff0000, v158
	v_lshlrev_b32_e32 v175, 16, v162
	v_and_b32_e32 v162, 0xffff0000, v162
	v_fmac_f32_e32 v160, v125, v156
	v_fmac_f32_e32 v161, v127, v157
	v_lshlrev_b32_e32 v172, 16, v159
	v_and_b32_e32 v159, 0xffff0000, v159
	v_lshlrev_b32_e32 v176, 16, v163
	v_and_b32_e32 v163, 0xffff0000, v163
	v_fmac_f32_e32 v173, v124, v149
	v_fmac_f32_e32 v175, v120, v171
	v_fmac_f32_e32 v162, v121, v158
	v_fmac_f32_e32 v174, v126, v170
	v_cvt_pk_bf16_f32 v120, v173, v160
	v_cvt_pk_bf16_f32 v121, v174, v161
	v_lshl_add_u64 v[160:161], s[36:37], 0, v[166:167]
	v_fmac_f32_e32 v176, v122, v172
	v_fmac_f32_e32 v163, v123, v159
	v_cvt_pk_bf16_f32 v122, v175, v162
	v_cvt_pk_bf16_f32 v123, v176, v163
	global_load_dwordx4 v[124:127], v[168:169], off
	global_load_dwordx4 v[156:159], v[160:161], off
	v_or_b32_e32 v162, 16, v148
	v_ashrrev_i32_e32 v163, 31, v162
	v_lshlrev_b64 v[162:163], 11, v[162:163]
	v_lshl_add_u64 v[162:163], v[162:163], 0, v[146:147]
	v_lshlrev_b64 v[162:163], 1, v[162:163]
	global_store_dwordx4 v[164:165], v[120:123], off
	v_lshl_add_u64 v[166:167], s[44:45], 0, v[162:163]
	s_waitcnt vmcnt(1)
	v_lshlrev_b32_e32 v149, 16, v156
	v_lshlrev_b32_e32 v120, 16, v124
	v_and_b32_e32 v121, 0xffff0000, v124
	v_lshlrev_b32_e32 v122, 16, v125
	v_and_b32_e32 v123, 0xffff0000, v125
	v_lshlrev_b32_e32 v124, 16, v126
	v_and_b32_e32 v125, 0xffff0000, v126
	v_lshlrev_b32_e32 v126, 16, v127
	v_and_b32_e32 v127, 0xffff0000, v127
	v_and_b32_e32 v156, 0xffff0000, v156
	v_lshlrev_b32_e32 v164, 16, v157
	v_and_b32_e32 v157, 0xffff0000, v157
	v_lshlrev_b32_e32 v165, 16, v158
	v_and_b32_e32 v158, 0xffff0000, v158
	v_lshlrev_b32_e32 v168, 16, v159
	v_and_b32_e32 v159, 0xffff0000, v159
	v_fmac_f32_e32 v149, v116, v120
	v_fmac_f32_e32 v165, v112, v124
	v_fmac_f32_e32 v156, v117, v121
	v_fmac_f32_e32 v158, v113, v125
	v_fmac_f32_e32 v164, v118, v122
	v_fmac_f32_e32 v168, v114, v126
	v_fmac_f32_e32 v157, v119, v123
	v_fmac_f32_e32 v159, v115, v127
	v_cvt_pk_bf16_f32 v112, v149, v156
	v_cvt_pk_bf16_f32 v113, v164, v157
	v_cvt_pk_bf16_f32 v114, v165, v158
	v_cvt_pk_bf16_f32 v115, v168, v159
	global_store_dwordx4 v[160:161], v[112:115], off
	v_lshl_add_u64 v[120:121], s[36:37], 0, v[162:163]
	global_load_dwordx4 v[112:115], v[166:167], off
	global_load_dwordx4 v[116:119], v[120:121], off
	v_or_b32_e32 v162, 0x100, v162
	v_lshl_add_u64 v[122:123], s[44:45], 0, v[162:163]
	s_waitcnt vmcnt(1)
	v_lshlrev_b32_e32 v124, 16, v112
	v_and_b32_e32 v112, 0xffff0000, v112
	v_lshlrev_b32_e32 v125, 16, v113
	v_and_b32_e32 v113, 0xffff0000, v113
	s_waitcnt vmcnt(0)
; __device__ __forceinline__ u32x4 pack8(f32x4 a, f32x4 b) { u32x4 o; o.x = pk2(a[0], a[1]); o.y = pk2(a[2], a[3]); o.z = pk2(b[0], b[1]); o.w = pk2(b[2], b[3]); return o; }
; __device__ __forceinline__ void unpack8(u32x4 v, f32x4& a, f32x4& b) { a[0] = bflo(v.x); a[1] = bfhi(v.x); a[2] = bflo(v.y); a[3] = bfhi(v.y); b[0] = bflo(v.z); b[1] = bfhi(v.z); b[2] = bflo(v.w); b[3] = bfhi(v.w); }
;     __device__ __forceinline__ void operator()(AccRef acc, const Unit& u, int wr, int wc, int fr, int fq) const {
;     ...
;                 for (int bj = 0; bj < 2; ++bj) { const size_t off = (size_t)(row0 + ai * 128 + m * 16) * 2048 + col0 + bj * 128;
;                     f32x4 g0, g1, o0, o1, a, b; unpack8(*(const u32x4*)(GB + off), g0, g1); unpack8(*(const u32x4*)(O + off), o0, o1);
; #pragma unroll
;                     for (int i = 0; i < 4; ++i) { a[i] = o0[i] + g0[i] * acc[ai][bj][m][0][i]; b[i] = o1[i] + g1[i] * acc[ai][bj][m][1][i]; }
;                     *(u32x4*)(O + off) = pack8(a, b); }
	v_lshlrev_b32_e32 v149, 16, v116
	v_and_b32_e32 v116, 0xffff0000, v116
	v_lshlrev_b32_e32 v156, 16, v117
	v_and_b32_e32 v117, 0xffff0000, v117
	v_lshlrev_b32_e32 v126, 16, v114
	v_and_b32_e32 v114, 0xffff0000, v114
	v_lshlrev_b32_e32 v157, 16, v118
	v_and_b32_e32 v118, 0xffff0000, v118
	v_fmac_f32_e32 v116, v109, v112
	v_fmac_f32_e32 v117, v111, v113
	v_lshlrev_b32_e32 v127, 16, v115
	v_and_b32_e32 v115, 0xffff0000, v115
	v_lshlrev_b32_e32 v158, 16, v119
	v_and_b32_e32 v119, 0xffff0000, v119
	v_fmac_f32_e32 v149, v108, v124
	v_fmac_f32_e32 v157, v104, v126
	v_fmac_f32_e32 v118, v105, v114
	v_fmac_f32_e32 v156, v110, v125
	v_cvt_pk_bf16_f32 v104, v149, v116
	v_cvt_pk_bf16_f32 v105, v156, v117
	v_lshl_add_u64 v[116:117], s[36:37], 0, v[162:163]
	v_fmac_f32_e32 v158, v106, v127
	v_fmac_f32_e32 v119, v107, v115
	v_cvt_pk_bf16_f32 v106, v157, v118
	v_cvt_pk_bf16_f32 v107, v158, v119
	global_load_dwordx4 v[108:111], v[122:123], off
	global_load_dwordx4 v[112:115], v[116:117], off
	v_or_b32_e32 v118, 32, v148
	v_ashrrev_i32_e32 v119, 31, v118
	v_lshlrev_b64 v[118:119], 11, v[118:119]
	v_lshl_add_u64 v[118:119], v[118:119], 0, v[146:147]
	v_lshlrev_b64 v[118:119], 1, v[118:119]
	global_store_dwordx4 v[120:121], v[104:107], off
	v_lshl_add_u64 v[122:123], s[44:45], 0, v[118:119]
	s_waitcnt vmcnt(1)
	v_lshlrev_b32_e32 v120, 16, v112
	v_lshlrev_b32_e32 v104, 16, v108
	v_and_b32_e32 v105, 0xffff0000, v108
	v_lshlrev_b32_e32 v106, 16, v109
	v_and_b32_e32 v107, 0xffff0000, v109
	v_lshlrev_b32_e32 v108, 16, v110
	v_and_b32_e32 v109, 0xffff0000, v110
	v_lshlrev_b32_e32 v110, 16, v111
	v_and_b32_e32 v111, 0xffff0000, v111
	v_and_b32_e32 v112, 0xffff0000, v112
	v_lshlrev_b32_e32 v121, 16, v113
	v_and_b32_e32 v113, 0xffff0000, v113
	v_lshlrev_b32_e32 v124, 16, v114
	v_and_b32_e32 v114, 0xffff0000, v114
	v_lshlrev_b32_e32 v125, 16, v115
	v_and_b32_e32 v115, 0xffff0000, v115
	v_fmac_f32_e32 v120, v100, v104
	v_fmac_f32_e32 v124, v96, v108
	v_fmac_f32_e32 v112, v101, v105
	v_fmac_f32_e32 v114, v97, v109
	v_fmac_f32_e32 v121, v102, v106
	v_fmac_f32_e32 v125, v98, v110
	v_fmac_f32_e32 v113, v103, v107
	v_fmac_f32_e32 v115, v99, v111
	v_cvt_pk_bf16_f32 v96, v120, v112
	v_cvt_pk_bf16_f32 v97, v121, v113
	v_cvt_pk_bf16_f32 v98, v124, v114
	v_cvt_pk_bf16_f32 v99, v125, v115
	global_store_dwordx4 v[116:117], v[96:99], off
	v_lshl_add_u64 v[104:105], s[36:37], 0, v[118:119]
	global_load_dwordx4 v[96:99], v[122:123], off
	global_load_dwordx4 v[100:103], v[104:105], off
	v_or_b32_e32 v118, 0x100, v118
	v_lshl_add_u64 v[106:107], s[44:45], 0, v[118:119]
	s_waitcnt vmcnt(1)
	v_lshlrev_b32_e32 v108, 16, v96
	v_and_b32_e32 v96, 0xffff0000, v96
	v_lshlrev_b32_e32 v109, 16, v97
	v_and_b32_e32 v97, 0xffff0000, v97
	s_waitcnt vmcnt(0)
	v_lshlrev_b32_e32 v112, 16, v100
	v_and_b32_e32 v100, 0xffff0000, v100
	v_lshlrev_b32_e32 v113, 16, v101
	v_and_b32_e32 v101, 0xffff0000, v101
	v_lshlrev_b32_e32 v110, 16, v98
	v_and_b32_e32 v98, 0xffff0000, v98
	v_lshlrev_b32_e32 v114, 16, v102
	v_and_b32_e32 v102, 0xffff0000, v102
	v_fmac_f32_e32 v100, v93, v96
	v_fmac_f32_e32 v101, v95, v97
	v_lshlrev_b32_e32 v111, 16, v99
	v_and_b32_e32 v99, 0xffff0000, v99
	v_lshlrev_b32_e32 v115, 16, v103
	v_and_b32_e32 v103, 0xffff0000, v103
	v_fmac_f32_e32 v112, v92, v108
	v_fmac_f32_e32 v114, v88, v110
	v_fmac_f32_e32 v102, v89, v98
	v_fmac_f32_e32 v113, v94, v109
	v_cvt_pk_bf16_f32 v88, v112, v100
	v_cvt_pk_bf16_f32 v89, v113, v101
	v_lshl_add_u64 v[100:101], s[36:37], 0, v[118:119]
	v_fmac_f32_e32 v115, v90, v111
	v_fmac_f32_e32 v103, v91, v99
	v_cvt_pk_bf16_f32 v90, v114, v102
	v_cvt_pk_bf16_f32 v91, v115, v103
	global_load_dwordx4 v[92:95], v[106:107], off
	global_load_dwordx4 v[96:99], v[100:101], off
	v_or_b32_e32 v102, 48, v148
	v_ashrrev_i32_e32 v103, 31, v102
	v_lshlrev_b64 v[102:103], 11, v[102:103]
	v_lshl_add_u64 v[102:103], v[102:103], 0, v[146:147]
	v_lshlrev_b64 v[102:103], 1, v[102:103]
	global_store_dwordx4 v[104:105], v[88:91], off
	v_lshl_add_u64 v[106:107], s[44:45], 0, v[102:103]
	s_waitcnt vmcnt(1)
	v_lshlrev_b32_e32 v104, 16, v96
	v_lshlrev_b32_e32 v88, 16, v92
	v_and_b32_e32 v89, 0xffff0000, v92
	v_lshlrev_b32_e32 v90, 16, v93
	v_and_b32_e32 v91, 0xffff0000, v93
	v_lshlrev_b32_e32 v92, 16, v94
	v_and_b32_e32 v93, 0xffff0000, v94
	v_lshlrev_b32_e32 v94, 16, v95
	v_and_b32_e32 v95, 0xffff0000, v95
	v_and_b32_e32 v96, 0xffff0000, v96
	v_lshlrev_b32_e32 v105, 16, v97
	v_and_b32_e32 v97, 0xffff0000, v97
	v_lshlrev_b32_e32 v108, 16, v98
	v_and_b32_e32 v98, 0xffff0000, v98
	v_lshlrev_b32_e32 v109, 16, v99
	v_and_b32_e32 v99, 0xffff0000, v99
	v_fmac_f32_e32 v104, v84, v88
	v_fmac_f32_e32 v108, v80, v92
	v_fmac_f32_e32 v96, v85, v89
	v_fmac_f32_e32 v98, v81, v93
	v_fmac_f32_e32 v105, v86, v90
	v_fmac_f32_e32 v109, v82, v94
	v_fmac_f32_e32 v97, v87, v91
	v_fmac_f32_e32 v99, v83, v95
	v_cvt_pk_bf16_f32 v80, v104, v96
	v_cvt_pk_bf16_f32 v81, v105, v97
	v_cvt_pk_bf16_f32 v82, v108, v98
	v_cvt_pk_bf16_f32 v83, v109, v99
	global_store_dwordx4 v[100:101], v[80:83], off
	v_lshl_add_u64 v[88:89], s[36:37], 0, v[102:103]
	global_load_dwordx4 v[80:83], v[106:107], off
	global_load_dwordx4 v[84:87], v[88:89], off
	v_or_b32_e32 v102, 0x100, v102
	v_lshl_add_u64 v[90:91], s[44:45], 0, v[102:103]
	s_waitcnt vmcnt(1)
	v_lshlrev_b32_e32 v92, 16, v80
	v_and_b32_e32 v80, 0xffff0000, v80
	v_lshlrev_b32_e32 v93, 16, v81
	v_and_b32_e32 v81, 0xffff0000, v81
	s_waitcnt vmcnt(0)
; __device__ __forceinline__ u32x4 pack8(f32x4 a, f32x4 b) { u32x4 o; o.x = pk2(a[0], a[1]); o.y = pk2(a[2], a[3]); o.z = pk2(b[0], b[1]); o.w = pk2(b[2], b[3]); return o; }
; __device__ __forceinline__ void unpack8(u32x4 v, f32x4& a, f32x4& b) { a[0] = bflo(v.x); a[1] = bfhi(v.x); a[2] = bflo(v.y); a[3] = bfhi(v.y); b[0] = bflo(v.z); b[1] = bfhi(v.z); b[2] = bflo(v.w); b[3] = bfhi(v.w); }
;     __device__ __forceinline__ void operator()(AccRef acc, const Unit& u, int wr, int wc, int fr, int fq) const {
;     ...
;                 for (int bj = 0; bj < 2; ++bj) { const size_t off = (size_t)(row0 + ai * 128 + m * 16) * 2048 + col0 + bj * 128;
;                     f32x4 g0, g1, o0, o1, a, b; unpack8(*(const u32x4*)(GB + off), g0, g1); unpack8(*(const u32x4*)(O + off), o0, o1);
; #pragma unroll
;                     for (int i = 0; i < 4; ++i) { a[i] = o0[i] + g0[i] * acc[ai][bj][m][0][i]; b[i] = o1[i] + g1[i] * acc[ai][bj][m][1][i]; }
;                     *(u32x4*)(O + off) = pack8(a, b); }
	v_lshlrev_b32_e32 v96, 16, v84
	v_and_b32_e32 v84, 0xffff0000, v84
	v_lshlrev_b32_e32 v97, 16, v85
	v_and_b32_e32 v85, 0xffff0000, v85
	v_lshlrev_b32_e32 v94, 16, v82
	v_and_b32_e32 v82, 0xffff0000, v82
	v_lshlrev_b32_e32 v98, 16, v86
	v_and_b32_e32 v86, 0xffff0000, v86
	v_fmac_f32_e32 v84, v77, v80
	v_fmac_f32_e32 v85, v79, v81
	v_lshlrev_b32_e32 v95, 16, v83
	v_and_b32_e32 v83, 0xffff0000, v83
	v_lshlrev_b32_e32 v99, 16, v87
	v_and_b32_e32 v87, 0xffff0000, v87
	v_fmac_f32_e32 v96, v76, v92
	v_fmac_f32_e32 v98, v72, v94
	v_fmac_f32_e32 v86, v73, v82
	v_fmac_f32_e32 v97, v78, v93
	v_cvt_pk_bf16_f32 v72, v96, v84
	v_cvt_pk_bf16_f32 v73, v97, v85
	v_lshl_add_u64 v[84:85], s[36:37], 0, v[102:103]
	v_fmac_f32_e32 v99, v74, v95
	v_fmac_f32_e32 v87, v75, v83
	v_cvt_pk_bf16_f32 v74, v98, v86
	v_cvt_pk_bf16_f32 v75, v99, v87
	global_load_dwordx4 v[76:79], v[90:91], off
	global_load_dwordx4 v[80:83], v[84:85], off
	v_lshl_add_u64 v[86:87], v[144:145], 0, s[42:43]
	global_store_dwordx4 v[88:89], v[72:75], off
	v_lshl_add_u64 v[90:91], s[44:45], 0, v[86:87]
	s_waitcnt vmcnt(1)
	v_lshlrev_b32_e32 v88, 16, v80
	v_lshlrev_b32_e32 v72, 16, v76
	v_and_b32_e32 v73, 0xffff0000, v76
	v_lshlrev_b32_e32 v74, 16, v77
	v_and_b32_e32 v75, 0xffff0000, v77
	v_lshlrev_b32_e32 v76, 16, v78
	v_and_b32_e32 v77, 0xffff0000, v78
	v_lshlrev_b32_e32 v78, 16, v79
	v_and_b32_e32 v79, 0xffff0000, v79
	v_and_b32_e32 v80, 0xffff0000, v80
	v_lshlrev_b32_e32 v89, 16, v81
	v_and_b32_e32 v81, 0xffff0000, v81
	v_lshlrev_b32_e32 v92, 16, v82
	v_and_b32_e32 v82, 0xffff0000, v82
	v_lshlrev_b32_e32 v93, 16, v83
	v_and_b32_e32 v83, 0xffff0000, v83
	v_fmac_f32_e32 v88, v68, v72
	v_fmac_f32_e32 v92, v64, v76
	v_fmac_f32_e32 v80, v69, v73
	v_fmac_f32_e32 v82, v65, v77
	v_fmac_f32_e32 v89, v70, v74
	v_fmac_f32_e32 v93, v66, v78
	v_fmac_f32_e32 v81, v71, v75
	v_fmac_f32_e32 v83, v67, v79
	v_cvt_pk_bf16_f32 v64, v88, v80
	v_cvt_pk_bf16_f32 v65, v89, v81
	v_cvt_pk_bf16_f32 v66, v92, v82
	v_cvt_pk_bf16_f32 v67, v93, v83
	global_store_dwordx4 v[84:85], v[64:67], off
	v_lshl_add_u64 v[72:73], s[36:37], 0, v[86:87]
	global_load_dwordx4 v[64:67], v[90:91], off
	global_load_dwordx4 v[68:71], v[72:73], off
	v_lshl_add_u64 v[74:75], v[144:145], 0, s[10:11]
	v_lshl_add_u64 v[76:77], s[44:45], 0, v[74:75]
	s_waitcnt vmcnt(1)
	v_lshlrev_b32_e32 v78, 16, v64
	v_and_b32_e32 v64, 0xffff0000, v64
	v_lshlrev_b32_e32 v79, 16, v65
	v_and_b32_e32 v65, 0xffff0000, v65
	s_waitcnt vmcnt(0)
	v_lshlrev_b32_e32 v82, 16, v68
	v_and_b32_e32 v68, 0xffff0000, v68
	v_lshlrev_b32_e32 v83, 16, v69
	v_and_b32_e32 v69, 0xffff0000, v69
	v_lshlrev_b32_e32 v80, 16, v66
	v_and_b32_e32 v66, 0xffff0000, v66
	v_lshlrev_b32_e32 v84, 16, v70
	v_and_b32_e32 v70, 0xffff0000, v70
	v_fmac_f32_e32 v68, v61, v64
	v_fmac_f32_e32 v69, v63, v65
	v_lshlrev_b32_e32 v81, 16, v67
	v_and_b32_e32 v67, 0xffff0000, v67
	v_lshlrev_b32_e32 v85, 16, v71
	v_and_b32_e32 v71, 0xffff0000, v71
	v_fmac_f32_e32 v82, v60, v78
	v_fmac_f32_e32 v84, v56, v80
	v_fmac_f32_e32 v70, v57, v66
	v_fmac_f32_e32 v83, v62, v79
	v_cvt_pk_bf16_f32 v56, v82, v68
	v_cvt_pk_bf16_f32 v57, v83, v69
	v_lshl_add_u64 v[68:69], s[36:37], 0, v[74:75]
	v_fmac_f32_e32 v85, v58, v81
	v_fmac_f32_e32 v71, v59, v67
	v_cvt_pk_bf16_f32 v58, v84, v70
	v_cvt_pk_bf16_f32 v59, v85, v71
	global_load_dwordx4 v[60:63], v[76:77], off
	global_load_dwordx4 v[64:67], v[68:69], off
	v_lshl_add_u64 v[70:71], v[144:145], 0, s[12:13]
	global_store_dwordx4 v[72:73], v[56:59], off
	v_lshl_add_u64 v[74:75], s[44:45], 0, v[70:71]
	s_waitcnt vmcnt(1)
	v_lshlrev_b32_e32 v72, 16, v64
	v_lshlrev_b32_e32 v56, 16, v60
	v_and_b32_e32 v57, 0xffff0000, v60
	v_lshlrev_b32_e32 v58, 16, v61
	v_and_b32_e32 v59, 0xffff0000, v61
	v_lshlrev_b32_e32 v60, 16, v62
	v_and_b32_e32 v61, 0xffff0000, v62
	v_lshlrev_b32_e32 v62, 16, v63
	v_and_b32_e32 v63, 0xffff0000, v63
	v_and_b32_e32 v64, 0xffff0000, v64
	v_lshlrev_b32_e32 v73, 16, v65
	v_and_b32_e32 v65, 0xffff0000, v65
	v_lshlrev_b32_e32 v76, 16, v66
	v_and_b32_e32 v66, 0xffff0000, v66
	v_lshlrev_b32_e32 v77, 16, v67
	v_and_b32_e32 v67, 0xffff0000, v67
	v_fmac_f32_e32 v72, v52, v56
	v_fmac_f32_e32 v76, v48, v60
	v_fmac_f32_e32 v64, v53, v57
	v_fmac_f32_e32 v66, v49, v61
	v_fmac_f32_e32 v73, v54, v58
	v_fmac_f32_e32 v77, v50, v62
	v_fmac_f32_e32 v65, v55, v59
	v_fmac_f32_e32 v67, v51, v63
	v_cvt_pk_bf16_f32 v48, v72, v64
	v_cvt_pk_bf16_f32 v49, v73, v65
	v_cvt_pk_bf16_f32 v50, v76, v66
	v_cvt_pk_bf16_f32 v51, v77, v67
	global_store_dwordx4 v[68:69], v[48:51], off
	v_lshl_add_u64 v[56:57], s[36:37], 0, v[70:71]
	global_load_dwordx4 v[48:51], v[74:75], off
	global_load_dwordx4 v[52:55], v[56:57], off
	v_lshl_add_u64 v[58:59], v[144:145], 0, s[14:15]
	v_lshl_add_u64 v[60:61], s[44:45], 0, v[58:59]
	s_waitcnt vmcnt(1)
	v_lshlrev_b32_e32 v62, 16, v48
	v_and_b32_e32 v48, 0xffff0000, v48
	v_lshlrev_b32_e32 v63, 16, v49
	v_and_b32_e32 v49, 0xffff0000, v49
	s_waitcnt vmcnt(0)
	v_lshlrev_b32_e32 v66, 16, v52
	v_and_b32_e32 v52, 0xffff0000, v52
	v_lshlrev_b32_e32 v67, 16, v53
	v_and_b32_e32 v53, 0xffff0000, v53
	v_lshlrev_b32_e32 v64, 16, v50
	v_and_b32_e32 v50, 0xffff0000, v50
	v_lshlrev_b32_e32 v68, 16, v54
	v_and_b32_e32 v54, 0xffff0000, v54
	v_fmac_f32_e32 v52, v45, v48
	v_fmac_f32_e32 v53, v47, v49
	v_lshlrev_b32_e32 v65, 16, v51
	v_and_b32_e32 v51, 0xffff0000, v51
	v_lshlrev_b32_e32 v69, 16, v55
	v_and_b32_e32 v55, 0xffff0000, v55
	v_fmac_f32_e32 v66, v44, v62
	v_fmac_f32_e32 v68, v40, v64
	v_fmac_f32_e32 v54, v41, v50
	v_fmac_f32_e32 v67, v46, v63
	v_cvt_pk_bf16_f32 v40, v66, v52
	v_cvt_pk_bf16_f32 v41, v67, v53
	v_lshl_add_u64 v[52:53], s[36:37], 0, v[58:59]
	v_fmac_f32_e32 v69, v42, v65
	v_fmac_f32_e32 v55, v43, v51
	v_cvt_pk_bf16_f32 v42, v68, v54
	v_cvt_pk_bf16_f32 v43, v69, v55
	global_load_dwordx4 v[44:47], v[60:61], off
	global_load_dwordx4 v[48:51], v[52:53], off
	v_lshl_add_u64 v[54:55], v[144:145], 0, s[20:21]
	global_store_dwordx4 v[56:57], v[40:43], off
	v_lshl_add_u64 v[58:59], s[44:45], 0, v[54:55]
	s_waitcnt vmcnt(1)
; #define PG8_BAR __builtin_amdgcn_s_barrier()
; __device__ __forceinline__ u32x4 pack8(f32x4 a, f32x4 b) { u32x4 o; o.x = pk2(a[0], a[1]); o.y = pk2(a[2], a[3]); o.z = pk2(b[0], b[1]); o.w = pk2(b[2], b[3]); return o; }
; __device__ __forceinline__ void unpack8(u32x4 v, f32x4& a, f32x4& b) { a[0] = bflo(v.x); a[1] = bfhi(v.x); a[2] = bflo(v.y); a[3] = bfhi(v.y); b[0] = bflo(v.z); b[1] = bfhi(v.z); b[2] = bflo(v.w); b[3] = bfhi(v.w); }
; template <bool LT, class Epi>
; __device__ __forceinline__ void gemm_phase(LAS unsigned char* lds, const Gemm g, const StaticOrder& S, const Epi& E) {
;     ...
;         if (!has_next) break;
; #pragma unroll
;         for (int a = 0; a < 2; ++a)
; #pragma unroll
;             for (int b = 0; b < 2; ++b)
; #pragma unroll
;                 for (int m = 0; m < 4; ++m)
; #pragma unroll
;                     for (int n = 0; n < 2; ++n) acc[a][b][m][n] = (f32x4){0.f, 0.f, 0.f, 0.f};
;         cur = nxt; cA = nA; cB = nB; ++ui;
;         if (wr == 1) PG8_BAR;
;     __device__ __forceinline__ void operator()(AccRef acc, const Unit& u, int wr, int wc, int fr, int fq) const {
;     ...
;                 for (int bj = 0; bj < 2; ++bj) { const size_t off = (size_t)(row0 + ai * 128 + m * 16) * 2048 + col0 + bj * 128;
;                     f32x4 g0, g1, o0, o1, a, b; unpack8(*(const u32x4*)(GB + off), g0, g1); unpack8(*(const u32x4*)(O + off), o0, o1);
; #pragma unroll
;                     for (int i = 0; i < 4; ++i) { a[i] = o0[i] + g0[i] * acc[ai][bj][m][0][i]; b[i] = o1[i] + g1[i] * acc[ai][bj][m][1][i]; }
;                     *(u32x4*)(O + off) = pack8(a, b); }
	v_lshlrev_b32_e32 v56, 16, v48
	v_lshlrev_b32_e32 v40, 16, v44
	v_and_b32_e32 v41, 0xffff0000, v44
	v_lshlrev_b32_e32 v42, 16, v45
	v_and_b32_e32 v43, 0xffff0000, v45
	v_lshlrev_b32_e32 v44, 16, v46
	v_and_b32_e32 v45, 0xffff0000, v46
	v_lshlrev_b32_e32 v46, 16, v47
	v_and_b32_e32 v47, 0xffff0000, v47
	v_and_b32_e32 v48, 0xffff0000, v48
	v_lshlrev_b32_e32 v57, 16, v49
	v_and_b32_e32 v49, 0xffff0000, v49
	v_lshlrev_b32_e32 v60, 16, v50
	v_and_b32_e32 v50, 0xffff0000, v50
	v_lshlrev_b32_e32 v61, 16, v51
	v_and_b32_e32 v51, 0xffff0000, v51
	v_fmac_f32_e32 v56, v36, v40
	v_fmac_f32_e32 v60, v32, v44
	v_fmac_f32_e32 v48, v37, v41
	v_fmac_f32_e32 v50, v33, v45
	v_fmac_f32_e32 v57, v38, v42
	v_fmac_f32_e32 v61, v34, v46
	v_fmac_f32_e32 v49, v39, v43
	v_fmac_f32_e32 v51, v35, v47
	v_cvt_pk_bf16_f32 v32, v56, v48
	v_cvt_pk_bf16_f32 v33, v57, v49
	v_cvt_pk_bf16_f32 v34, v60, v50
	v_cvt_pk_bf16_f32 v35, v61, v51
	global_store_dwordx4 v[52:53], v[32:35], off
	v_lshl_add_u64 v[40:41], s[36:37], 0, v[54:55]
	global_load_dwordx4 v[32:35], v[58:59], off
	global_load_dwordx4 v[36:39], v[40:41], off
	v_lshl_add_u64 v[42:43], v[144:145], 0, s[24:25]
	v_lshl_add_u64 v[44:45], s[44:45], 0, v[42:43]
	s_waitcnt vmcnt(1)
	v_lshlrev_b32_e32 v46, 16, v32
	v_and_b32_e32 v32, 0xffff0000, v32
	v_lshlrev_b32_e32 v47, 16, v33
	v_and_b32_e32 v33, 0xffff0000, v33
	s_waitcnt vmcnt(0)
	v_lshlrev_b32_e32 v50, 16, v36
	v_and_b32_e32 v36, 0xffff0000, v36
	v_lshlrev_b32_e32 v51, 16, v37
	v_and_b32_e32 v37, 0xffff0000, v37
	v_lshlrev_b32_e32 v48, 16, v34
	v_and_b32_e32 v34, 0xffff0000, v34
	v_lshlrev_b32_e32 v52, 16, v38
	v_and_b32_e32 v38, 0xffff0000, v38
	v_fmac_f32_e32 v36, v29, v32
	v_fmac_f32_e32 v37, v31, v33
	v_lshlrev_b32_e32 v49, 16, v35
	v_and_b32_e32 v35, 0xffff0000, v35
	v_lshlrev_b32_e32 v53, 16, v39
	v_and_b32_e32 v39, 0xffff0000, v39
	v_fmac_f32_e32 v50, v28, v46
	v_fmac_f32_e32 v52, v24, v48
	v_fmac_f32_e32 v38, v25, v34
	v_fmac_f32_e32 v51, v30, v47
	v_cvt_pk_bf16_f32 v24, v50, v36
	v_cvt_pk_bf16_f32 v25, v51, v37
	v_lshl_add_u64 v[36:37], s[36:37], 0, v[42:43]
	v_fmac_f32_e32 v53, v26, v49
	v_fmac_f32_e32 v39, v27, v35
	v_cvt_pk_bf16_f32 v26, v52, v38
	v_cvt_pk_bf16_f32 v27, v53, v39
	global_load_dwordx4 v[28:31], v[44:45], off
	global_load_dwordx4 v[32:35], v[36:37], off
	v_lshl_add_u64 v[38:39], v[144:145], 0, s[34:35]
	global_store_dwordx4 v[40:41], v[24:27], off
	v_lshl_add_u64 v[42:43], s[44:45], 0, v[38:39]
	s_waitcnt vmcnt(1)
	v_lshlrev_b32_e32 v40, 16, v32
	v_lshlrev_b32_e32 v24, 16, v28
	v_and_b32_e32 v25, 0xffff0000, v28
	v_lshlrev_b32_e32 v26, 16, v29
	v_and_b32_e32 v27, 0xffff0000, v29
	v_lshlrev_b32_e32 v28, 16, v30
	v_and_b32_e32 v29, 0xffff0000, v30
	v_lshlrev_b32_e32 v30, 16, v31
	v_and_b32_e32 v31, 0xffff0000, v31
	v_and_b32_e32 v32, 0xffff0000, v32
	v_lshlrev_b32_e32 v41, 16, v33
	v_and_b32_e32 v33, 0xffff0000, v33
	v_lshlrev_b32_e32 v44, 16, v34
	v_and_b32_e32 v34, 0xffff0000, v34
	v_lshlrev_b32_e32 v45, 16, v35
	v_and_b32_e32 v35, 0xffff0000, v35
	v_fmac_f32_e32 v40, v20, v24
	v_fmac_f32_e32 v44, v16, v28
	v_fmac_f32_e32 v32, v21, v25
	v_fmac_f32_e32 v34, v17, v29
	v_fmac_f32_e32 v41, v22, v26
	v_fmac_f32_e32 v45, v18, v30
	v_fmac_f32_e32 v33, v23, v27
	v_fmac_f32_e32 v35, v19, v31
	v_cvt_pk_bf16_f32 v16, v40, v32
	v_cvt_pk_bf16_f32 v17, v41, v33
	v_cvt_pk_bf16_f32 v18, v44, v34
	v_cvt_pk_bf16_f32 v19, v45, v35
	global_store_dwordx4 v[36:37], v[16:19], off
	v_lshl_add_u64 v[24:25], s[36:37], 0, v[38:39]
	global_load_dwordx4 v[16:19], v[42:43], off
	global_load_dwordx4 v[20:23], v[24:25], off
	v_lshl_add_u64 v[26:27], v[144:145], 0, s[46:47]
	v_lshl_add_u64 v[28:29], s[44:45], 0, v[26:27]
	s_waitcnt vmcnt(1)
	v_lshlrev_b32_e32 v30, 16, v16
	v_and_b32_e32 v16, 0xffff0000, v16
	v_lshlrev_b32_e32 v31, 16, v17
	v_and_b32_e32 v17, 0xffff0000, v17
	s_waitcnt vmcnt(0)
	v_lshlrev_b32_e32 v34, 16, v20
	v_and_b32_e32 v20, 0xffff0000, v20
	v_lshlrev_b32_e32 v35, 16, v21
	v_and_b32_e32 v21, 0xffff0000, v21
	v_lshlrev_b32_e32 v32, 16, v18
	v_and_b32_e32 v18, 0xffff0000, v18
	v_lshlrev_b32_e32 v36, 16, v22
	v_and_b32_e32 v22, 0xffff0000, v22
	v_fmac_f32_e32 v20, v13, v16
	v_fmac_f32_e32 v21, v15, v17
	v_lshlrev_b32_e32 v33, 16, v19
	v_and_b32_e32 v19, 0xffff0000, v19
	v_lshlrev_b32_e32 v37, 16, v23
	v_and_b32_e32 v23, 0xffff0000, v23
	v_fmac_f32_e32 v34, v12, v30
	v_fmac_f32_e32 v36, v8, v32
	v_fmac_f32_e32 v22, v9, v18
	v_fmac_f32_e32 v35, v14, v31
	v_cvt_pk_bf16_f32 v8, v34, v20
	v_cvt_pk_bf16_f32 v9, v35, v21
	v_lshl_add_u64 v[20:21], s[36:37], 0, v[26:27]
	v_fmac_f32_e32 v37, v10, v33
	v_fmac_f32_e32 v23, v11, v19
	v_cvt_pk_bf16_f32 v10, v36, v22
	v_cvt_pk_bf16_f32 v11, v37, v23
	global_load_dwordx4 v[12:15], v[28:29], off
	global_load_dwordx4 v[16:19], v[20:21], off
	s_waitcnt vmcnt(0)
	v_lshlrev_b32_e32 v22, 16, v16
	global_store_dwordx4 v[24:25], v[8:11], off
	v_and_b32_e32 v16, 0xffff0000, v16
	v_lshlrev_b32_e32 v23, 16, v17
	v_lshlrev_b32_e32 v8, 16, v12
	v_and_b32_e32 v9, 0xffff0000, v12
	v_lshlrev_b32_e32 v10, 16, v13
	v_and_b32_e32 v11, 0xffff0000, v13
	v_lshlrev_b32_e32 v12, 16, v14
	v_and_b32_e32 v13, 0xffff0000, v14
	v_lshlrev_b32_e32 v14, 16, v15
	v_and_b32_e32 v15, 0xffff0000, v15
	v_and_b32_e32 v17, 0xffff0000, v17
	v_lshlrev_b32_e32 v24, 16, v18
	v_and_b32_e32 v18, 0xffff0000, v18
	v_lshlrev_b32_e32 v25, 16, v19
	v_and_b32_e32 v19, 0xffff0000, v19
	v_fmac_f32_e32 v22, v4, v8
	v_fmac_f32_e32 v24, v0, v12
	v_fmac_f32_e32 v16, v5, v9
	v_fmac_f32_e32 v18, v1, v13
	v_fmac_f32_e32 v23, v6, v10
	v_fmac_f32_e32 v25, v2, v14
	v_fmac_f32_e32 v17, v7, v11
	v_fmac_f32_e32 v19, v3, v15
	v_cvt_pk_bf16_f32 v0, v22, v16
	v_cvt_pk_bf16_f32 v1, v23, v17
	v_cvt_pk_bf16_f32 v2, v24, v18
	v_cvt_pk_bf16_f32 v3, v25, v19
	global_store_dwordx4 v[20:21], v[0:3], off
	s_cbranch_vccnz .LBB0_1692
	s_andn2_b64 vcc, exec, s[4:5]
	s_cbranch_vccnz .LBB0_1691
	s_barrier
	s_branch .LBB0_1691
